# v35 + first K-fragment reads above the active branches + dead VALU->MFMA pad removed (stack of v36 and v37)
# baseline (speedup 1.0000x reference)
; #define LAS __attribute__((address_space(3)))
; template <int HF> ...
;     ...
;         for (int r = 0; r < 16; ++r) p[r] = __builtin_fmaf(s2v, (float)((r & 3) + 8 * (r >> 2)), tb);
; #pragma unroll
;         for (int d0 = 0; d0 < 4; ++d0) { const bf16x8 kf = *(const LAS bf16x8*)(kb + HF * 32 * KROW + sub * 128 + d0 * 32);
;             p = __builtin_amdgcn_mfma_f32_32x32x16_bf16(kf, qf[sub][d0], p, 0, 0, 0); }
;         if (band) { const int lim = qw0 + r32 - (kvh0 + 4 * hi);
;             asm volatile("s_nop 15" : "+v"(p));
;             const float ninf = -INFINITY;
; #pragma unroll
;             for (int r = 0; r < 16; ++r) asm("v_cmp_gt_i32_e32 vcc, %2, %1\n\tv_cndmask_b32_e32 %0, %0, %3, vcc" : "+v"(p[r]) : "v"(lim), "i"((r & 3) + 8 * (r >> 2)), "v"(ninf) : "vcc"); }
.LBB0_251:
	s_andn2_b64 vcc, exec, s[66:67]
	s_cbranch_vccnz .LBB0_259
	s_and_b64 vcc, exec, s[10:11]
	s_waitcnt vmcnt(7) lgkmcnt(1)
	v_mfma_f32_32x32x16_bf16 v[144:159], v[248:251], v[176:179], v[128:143]
	s_waitcnt vmcnt(6) lgkmcnt(0)
	v_mfma_f32_32x32x16_bf16 v[144:159], v[252:255], v[180:183], v[144:159]
	ds_read_b128 v[248:251], v247 offset:64
	ds_read_b128 v[252:255], v247 offset:96
	s_waitcnt vmcnt(5) lgkmcnt(1)
	v_mfma_f32_32x32x16_bf16 v[144:159], v[248:251], v[184:187], v[144:159]
	s_waitcnt vmcnt(4) lgkmcnt(0)
	v_mfma_f32_32x32x16_bf16 v[144:159], v[252:255], v[188:191], v[144:159]
	s_cbranch_vccnz .LBB0_254
	s_nop 15
	s_nop 0
	v_cmp_gt_i32_e32 vcc, 0, v227
	v_cndmask_b32_e32 v144, v144, v244, vcc
	s_nop 0
	v_cmp_gt_i32_e32 vcc, 1, v227
	v_cndmask_b32_e32 v145, v145, v244, vcc
	s_nop 0
	v_cmp_gt_i32_e32 vcc, 2, v227
	v_cndmask_b32_e32 v146, v146, v244, vcc
	s_nop 0
	v_cmp_gt_i32_e32 vcc, 3, v227
	v_cndmask_b32_e32 v147, v147, v244, vcc
	s_nop 0
	v_cmp_gt_i32_e32 vcc, 8, v227
	v_cndmask_b32_e32 v148, v148, v244, vcc
	s_nop 0
	v_cmp_gt_i32_e32 vcc, 9, v227
	v_cndmask_b32_e32 v149, v149, v244, vcc
	s_nop 0
	v_cmp_gt_i32_e32 vcc, 10, v227
	v_cndmask_b32_e32 v150, v150, v244, vcc
	s_nop 0
	v_cmp_gt_i32_e32 vcc, 11, v227
	v_cndmask_b32_e32 v151, v151, v244, vcc
	s_nop 0
	v_cmp_gt_i32_e32 vcc, 16, v227
	v_cndmask_b32_e32 v152, v152, v244, vcc
	s_nop 0
	v_cmp_gt_i32_e32 vcc, 17, v227
	v_cndmask_b32_e32 v153, v153, v244, vcc
	s_nop 0
	v_cmp_gt_i32_e32 vcc, 18, v227
	v_cndmask_b32_e32 v154, v154, v244, vcc
	s_nop 0
	v_cmp_gt_i32_e32 vcc, 19, v227
	v_cndmask_b32_e32 v155, v155, v244, vcc
	s_nop 0
	v_cmp_gt_i32_e32 vcc, 24, v227
	v_cndmask_b32_e32 v156, v156, v244, vcc
	s_nop 0
	v_cmp_gt_i32_e32 vcc, 25, v227
	v_cndmask_b32_e32 v157, v157, v244, vcc
	s_nop 0
	v_cmp_gt_i32_e32 vcc, 26, v227
	v_cndmask_b32_e32 v158, v158, v244, vcc
	s_nop 0
	v_cmp_gt_i32_e32 vcc, 27, v227
	v_cndmask_b32_e32 v159, v159, v244, vcc
